# ff1 epilogue: canonicalize+relu v_max pairs fused into one v_max (bit-identical), store-data WAR pads kept
# speedup vs baseline: 1.0098x; 1.0098x over previous
.LBB0_1225:
	s_and_b64 vcc, exec, s[40:41]
	s_cbranch_vccz .Llast_ff1
	v_max_f32_e32 v124, v124, v124
	v_lshl_add_u32 v148, s48, 8, v1
	v_max_f32_e32 v124, 0, v124
	v_max_f32_e32 v125, v125, v125
	v_max_f32_e32 v126, v126, v126
	v_lshl_or_b32 v142, s47, 8, v145
	v_ashrrev_i32_e32 v149, 31, v148
	v_readlane_b32 s2, v246, 29
	v_mul_f32_e32 v147, v124, v124
	v_max_f32_e32 v124, v129, v129
	v_max_f32_e32 v125, 0, v125
	v_max_f32_e32 v126, 0, v126
	v_ashrrev_i32_e32 v143, 31, v142
	v_lshlrev_b64 v[150:151], 14, v[148:149]
	v_readlane_b32 s3, v246, 30
	v_max_f32_e32 v124, 0, v124
	v_mul_f32_e32 v129, v125, v125
	v_max_f32_e32 v125, v130, v130
	v_mul_f32_e32 v130, v126, v126
	v_lshl_add_u64 v[150:151], s[2:3], 0, v[150:151]
	v_lshlrev_b64 v[152:153], 1, v[142:143]
	v_max_f32_e32 v128, 0, v128
	v_mul_f32_e32 v124, v124, v124
	v_max_f32_e32 v125, 0, v125
	v_max_f32_e32 v126, 0, v131
	v_max_f32_e32 v127, 0, v127
	v_lshl_add_u64 v[142:143], v[150:151], 0, v[152:153]
	v_mul_f32_e32 v128, v128, v128
	v_mul_f32_e32 v125, v125, v125
	v_mul_f32_e32 v126, v126, v126
	v_mul_f32_e32 v127, v127, v127
	v_cvt_pk_bf16_f32 v124, v128, v124
	v_max_f32_e32 v116, 0, v116
	v_cvt_pk_bf16_f32 v125, v125, v126
	v_cvt_pk_bf16_f32 v126, v147, v129
	v_cvt_pk_bf16_f32 v127, v130, v127
	global_store_dwordx4 v[142:143], v[124:127], off
	v_max_f32_e32 v117, 0, v117
	v_max_f32_e32 v118, 0, v118
	v_mul_f32_e32 v124, v116, v116
	v_max_f32_e32 v116, 0, v121
	v_mul_f32_e32 v121, v117, v117
	v_max_f32_e32 v117, v122, v122
	v_mul_f32_e32 v122, v118, v118
	v_max_f32_e32 v120, 0, v120
	v_mul_f32_e32 v116, v116, v116
	v_max_f32_e32 v117, 0, v117
	v_max_f32_e32 v118, 0, v123
	v_max_f32_e32 v119, 0, v119
	v_mul_f32_e32 v120, v120, v120
	v_mul_f32_e32 v117, v117, v117
	v_mul_f32_e32 v118, v118, v118
	v_mul_f32_e32 v119, v119, v119
	v_cvt_pk_bf16_f32 v116, v120, v116
	v_cvt_pk_bf16_f32 v117, v117, v118
	v_cvt_pk_bf16_f32 v118, v124, v121
	v_cvt_pk_bf16_f32 v119, v122, v119
	global_store_dwordx4 v[142:143], v[116:119], off offset:256
	v_max_f32_e32 v108, 0, v108
	s_nop 0
	v_or_b32_e32 v116, 16, v148
	v_ashrrev_i32_e32 v117, 31, v116
	v_mul_f32_e32 v118, v108, v108
	v_max_f32_e32 v109, 0, v109
	v_max_f32_e32 v110, 0, v110
	v_lshlrev_b64 v[116:117], 14, v[116:117]
	v_max_f32_e32 v108, 0, v113
	v_mul_f32_e32 v113, v109, v109
	v_max_f32_e32 v109, v114, v114
	v_mul_f32_e32 v114, v110, v110
	v_lshl_add_u64 v[116:117], s[2:3], 0, v[116:117]
	v_max_f32_e32 v112, 0, v112
	v_mul_f32_e32 v108, v108, v108
	v_max_f32_e32 v109, 0, v109
	v_max_f32_e32 v110, 0, v115
	v_max_f32_e32 v111, 0, v111
	v_lshl_add_u64 v[116:117], v[116:117], 0, v[152:153]
	v_mul_f32_e32 v112, v112, v112
	v_mul_f32_e32 v109, v109, v109
	v_mul_f32_e32 v110, v110, v110
	v_mul_f32_e32 v111, v111, v111
	v_cvt_pk_bf16_f32 v108, v112, v108
	v_max_f32_e32 v100, 0, v100
	v_cvt_pk_bf16_f32 v109, v109, v110
	v_cvt_pk_bf16_f32 v110, v118, v113
	v_cvt_pk_bf16_f32 v111, v114, v111
	global_store_dwordx4 v[116:117], v[108:111], off
	v_max_f32_e32 v101, 0, v101
	v_max_f32_e32 v102, 0, v102
	v_mul_f32_e32 v108, v100, v100
	v_max_f32_e32 v100, 0, v105
	v_mul_f32_e32 v105, v101, v101
	v_max_f32_e32 v101, v106, v106
	v_mul_f32_e32 v106, v102, v102
	v_max_f32_e32 v104, 0, v104
	v_mul_f32_e32 v100, v100, v100
	v_max_f32_e32 v101, 0, v101
	v_max_f32_e32 v102, 0, v107
	v_max_f32_e32 v103, 0, v103
	v_mul_f32_e32 v104, v104, v104
	v_mul_f32_e32 v101, v101, v101
	v_mul_f32_e32 v102, v102, v102
	v_mul_f32_e32 v103, v103, v103
	v_cvt_pk_bf16_f32 v100, v104, v100
	v_cvt_pk_bf16_f32 v101, v101, v102
	v_cvt_pk_bf16_f32 v102, v108, v105
	v_cvt_pk_bf16_f32 v103, v106, v103
	global_store_dwordx4 v[116:117], v[100:103], off offset:256
	v_max_f32_e32 v92, 0, v92
	s_nop 0
	v_or_b32_e32 v100, 32, v148
	v_ashrrev_i32_e32 v101, 31, v100
	v_mul_f32_e32 v102, v92, v92
	v_max_f32_e32 v93, 0, v93
	v_max_f32_e32 v94, 0, v94
	v_lshlrev_b64 v[100:101], 14, v[100:101]
	v_max_f32_e32 v92, 0, v97
	v_mul_f32_e32 v97, v93, v93
	v_max_f32_e32 v93, v98, v98
	v_mul_f32_e32 v98, v94, v94
	v_lshl_add_u64 v[100:101], s[2:3], 0, v[100:101]
	v_max_f32_e32 v96, 0, v96
	v_mul_f32_e32 v92, v92, v92
	v_max_f32_e32 v93, 0, v93
	v_max_f32_e32 v94, 0, v99
	v_max_f32_e32 v95, 0, v95
	v_lshl_add_u64 v[100:101], v[100:101], 0, v[152:153]
	v_mul_f32_e32 v96, v96, v96
	v_mul_f32_e32 v93, v93, v93
	v_mul_f32_e32 v94, v94, v94
	v_mul_f32_e32 v95, v95, v95
	v_cvt_pk_bf16_f32 v92, v96, v92
	v_max_f32_e32 v84, 0, v84
	v_cvt_pk_bf16_f32 v93, v93, v94
	v_cvt_pk_bf16_f32 v94, v102, v97
	v_cvt_pk_bf16_f32 v95, v98, v95
	global_store_dwordx4 v[100:101], v[92:95], off
	v_max_f32_e32 v85, 0, v85
	v_max_f32_e32 v86, 0, v86
	v_mul_f32_e32 v92, v84, v84
	v_max_f32_e32 v84, 0, v89
	v_mul_f32_e32 v89, v85, v85
	v_max_f32_e32 v85, v90, v90
	v_mul_f32_e32 v90, v86, v86
	v_max_f32_e32 v88, 0, v88
	v_mul_f32_e32 v84, v84, v84
	v_max_f32_e32 v85, 0, v85
	v_max_f32_e32 v86, 0, v91
	v_max_f32_e32 v87, 0, v87
	v_mul_f32_e32 v88, v88, v88
	v_mul_f32_e32 v85, v85, v85
	v_mul_f32_e32 v86, v86, v86
	v_mul_f32_e32 v87, v87, v87
	v_cvt_pk_bf16_f32 v84, v88, v84
	v_cvt_pk_bf16_f32 v85, v85, v86
	v_cvt_pk_bf16_f32 v86, v92, v89
	v_cvt_pk_bf16_f32 v87, v90, v87
	global_store_dwordx4 v[100:101], v[84:87], off offset:256
	v_max_f32_e32 v76, 0, v76
	s_nop 0
	v_or_b32_e32 v84, 48, v148
	v_ashrrev_i32_e32 v85, 31, v84
	v_mul_f32_e32 v86, v76, v76
	v_max_f32_e32 v77, 0, v77
	v_max_f32_e32 v78, 0, v78
	v_lshlrev_b64 v[84:85], 14, v[84:85]
	v_max_f32_e32 v76, 0, v81
	v_mul_f32_e32 v81, v77, v77
	v_max_f32_e32 v77, v82, v82
	v_mul_f32_e32 v82, v78, v78
	v_lshl_add_u64 v[84:85], s[2:3], 0, v[84:85]
	v_max_f32_e32 v80, 0, v80
	v_mul_f32_e32 v76, v76, v76
	v_max_f32_e32 v77, 0, v77
	v_max_f32_e32 v78, 0, v83
	v_max_f32_e32 v79, 0, v79
	v_lshl_add_u64 v[84:85], v[84:85], 0, v[152:153]
	v_mul_f32_e32 v80, v80, v80
	v_mul_f32_e32 v77, v77, v77
	v_mul_f32_e32 v78, v78, v78
	v_mul_f32_e32 v79, v79, v79
	v_cvt_pk_bf16_f32 v76, v80, v76
	v_max_f32_e32 v68, 0, v68
	v_max_f32_e32 v69, 0, v69
	v_max_f32_e32 v70, 0, v70
	v_cvt_pk_bf16_f32 v77, v77, v78
	v_cvt_pk_bf16_f32 v78, v86, v81
	v_cvt_pk_bf16_f32 v79, v82, v79
	global_store_dwordx4 v[84:85], v[76:79], off
	s_nop 1
	v_mul_f32_e32 v76, v68, v68
	v_max_f32_e32 v68, v73, v73
	v_mul_f32_e32 v73, v69, v69
	v_max_f32_e32 v69, v74, v74
	v_mul_f32_e32 v74, v70, v70
	v_max_f32_e32 v68, 0, v68
	v_max_f32_e32 v69, 0, v69
	v_max_f32_e32 v70, 0, v75
	v_max_f32_e32 v72, 0, v72
	v_mul_f32_e32 v68, v68, v68
	v_mul_f32_e32 v69, v69, v69
	v_max_f32_e32 v71, 0, v71
	v_mul_f32_e32 v70, v70, v70
	v_mul_f32_e32 v72, v72, v72
	v_mul_f32_e32 v71, v71, v71
	v_cvt_pk_bf16_f32 v68, v72, v68
	v_cvt_pk_bf16_f32 v69, v69, v70
	v_cvt_pk_bf16_f32 v70, v76, v73
	v_max_f32_e32 v60, 0, v60
	v_cvt_pk_bf16_f32 v71, v74, v71
	global_store_dwordx4 v[84:85], v[68:71], off offset:256
	v_max_f32_e32 v61, 0, v61
	s_nop 0
	v_mul_f32_e32 v70, v60, v60
	v_max_f32_e32 v62, 0, v62
	v_max_f32_e32 v64, 0, v64
	v_max_f32_e32 v60, 0, v65
	v_mul_f32_e32 v65, v61, v61
	v_max_f32_e32 v61, v66, v66
	v_mul_f32_e32 v66, v62, v62
	v_mul_f32_e32 v64, v64, v64
	v_mul_f32_e32 v60, v60, v60
	v_max_f32_e32 v61, 0, v61
	v_max_f32_e32 v62, 0, v67
	s_mov_b32 s11, 0x200000
	v_mul_f32_e32 v61, v61, v61
	v_max_f32_e32 v63, 0, v63
	v_mul_f32_e32 v62, v62, v62
	v_cvt_pk_bf16_f32 v60, v64, v60
	v_add_co_u32_e32 v64, vcc, s11, v142
	v_mul_f32_e32 v63, v63, v63
	v_cvt_pk_bf16_f32 v61, v61, v62
	v_cvt_pk_bf16_f32 v62, v70, v65
	v_addc_co_u32_e32 v65, vcc, 0, v143, vcc
	v_max_f32_e32 v52, 0, v52
	v_max_f32_e32 v53, 0, v53
	v_max_f32_e32 v54, 0, v54
	v_cvt_pk_bf16_f32 v63, v66, v63
	global_store_dwordx4 v[64:65], v[60:63], off
	s_nop 1
	v_mul_f32_e32 v60, v52, v52
	v_max_f32_e32 v52, v57, v57
	v_mul_f32_e32 v57, v53, v53
	v_max_f32_e32 v53, v58, v58
	v_mul_f32_e32 v58, v54, v54
	v_max_f32_e32 v52, 0, v52
	v_max_f32_e32 v53, 0, v53
	v_max_f32_e32 v54, 0, v59
	s_mov_b64 s[18:19], 0x200000
	v_max_f32_e32 v56, 0, v56
	v_mul_f32_e32 v52, v52, v52
	v_mul_f32_e32 v53, v53, v53
	v_max_f32_e32 v55, 0, v55
	v_mul_f32_e32 v54, v54, v54
	v_lshl_add_u64 v[68:69], v[142:143], 0, s[18:19]
	v_mul_f32_e32 v56, v56, v56
	v_mul_f32_e32 v55, v55, v55
	v_cvt_pk_bf16_f32 v52, v56, v52
	v_cvt_pk_bf16_f32 v53, v53, v54
	v_cvt_pk_bf16_f32 v54, v60, v57
	v_max_f32_e32 v44, 0, v44
	v_cvt_pk_bf16_f32 v55, v58, v55
	global_store_dwordx4 v[68:69], v[52:55], off offset:256
	v_max_f32_e32 v45, 0, v45
	s_nop 0
	v_mul_f32_e32 v54, v44, v44
	v_max_f32_e32 v46, 0, v46
	v_max_f32_e32 v48, 0, v48
	v_max_f32_e32 v44, 0, v49
	v_mul_f32_e32 v49, v45, v45
	v_max_f32_e32 v45, v50, v50
	v_mul_f32_e32 v50, v46, v46
	v_mul_f32_e32 v48, v48, v48
	v_mul_f32_e32 v44, v44, v44
	v_max_f32_e32 v45, 0, v45
	v_max_f32_e32 v46, 0, v51
	s_mov_b32 s11, 0x240000
	v_mul_f32_e32 v45, v45, v45
	v_max_f32_e32 v47, 0, v47
	v_mul_f32_e32 v46, v46, v46
	v_cvt_pk_bf16_f32 v44, v48, v44
	v_add_co_u32_e32 v48, vcc, s11, v142
	v_mul_f32_e32 v47, v47, v47
	v_cvt_pk_bf16_f32 v45, v45, v46
	v_cvt_pk_bf16_f32 v46, v54, v49
	v_addc_co_u32_e32 v49, vcc, 0, v143, vcc
	v_max_f32_e32 v36, 0, v36
	v_max_f32_e32 v37, 0, v37
	v_max_f32_e32 v38, 0, v38
	v_cvt_pk_bf16_f32 v47, v50, v47
	global_store_dwordx4 v[48:49], v[44:47], off
	s_nop 1
	v_mul_f32_e32 v44, v36, v36
	v_max_f32_e32 v36, v41, v41
	v_mul_f32_e32 v41, v37, v37
	v_max_f32_e32 v37, v42, v42
	v_mul_f32_e32 v42, v38, v38
	v_max_f32_e32 v36, 0, v36
	v_max_f32_e32 v37, 0, v37
	v_max_f32_e32 v38, 0, v43
	s_mov_b64 s[18:19], 0x240000
	v_max_f32_e32 v40, 0, v40
	v_mul_f32_e32 v36, v36, v36
	v_mul_f32_e32 v37, v37, v37
	v_max_f32_e32 v39, 0, v39
	v_mul_f32_e32 v38, v38, v38
	v_lshl_add_u64 v[52:53], v[142:143], 0, s[18:19]
	v_mul_f32_e32 v40, v40, v40
	v_mul_f32_e32 v39, v39, v39
	v_cvt_pk_bf16_f32 v36, v40, v36
	v_cvt_pk_bf16_f32 v37, v37, v38
	v_cvt_pk_bf16_f32 v38, v44, v41
	v_max_f32_e32 v28, 0, v28
	v_cvt_pk_bf16_f32 v39, v42, v39
	global_store_dwordx4 v[52:53], v[36:39], off offset:256
	v_max_f32_e32 v29, 0, v29
	s_nop 0
	v_mul_f32_e32 v38, v28, v28
	v_max_f32_e32 v30, 0, v30
	v_max_f32_e32 v32, 0, v32
	v_max_f32_e32 v28, 0, v33
	v_mul_f32_e32 v33, v29, v29
	v_max_f32_e32 v29, v34, v34
	v_mul_f32_e32 v34, v30, v30
	v_mul_f32_e32 v32, v32, v32
	v_mul_f32_e32 v28, v28, v28
	v_max_f32_e32 v29, 0, v29
	v_max_f32_e32 v30, 0, v35
	s_mov_b32 s11, 0x280000
	v_mul_f32_e32 v29, v29, v29
	v_max_f32_e32 v31, 0, v31
	v_mul_f32_e32 v30, v30, v30
	v_cvt_pk_bf16_f32 v28, v32, v28
	v_add_co_u32_e32 v32, vcc, s11, v142
	v_mul_f32_e32 v31, v31, v31
	v_cvt_pk_bf16_f32 v29, v29, v30
	v_cvt_pk_bf16_f32 v30, v38, v33
	v_addc_co_u32_e32 v33, vcc, 0, v143, vcc
	v_max_f32_e32 v20, 0, v20
	v_max_f32_e32 v21, 0, v21
	v_max_f32_e32 v22, 0, v22
	v_cvt_pk_bf16_f32 v31, v34, v31
	global_store_dwordx4 v[32:33], v[28:31], off
	s_nop 1
	v_mul_f32_e32 v28, v20, v20
	v_max_f32_e32 v20, v25, v25
	v_mul_f32_e32 v25, v21, v21
	v_max_f32_e32 v21, v26, v26
	v_mul_f32_e32 v26, v22, v22
	v_max_f32_e32 v20, 0, v20
	v_max_f32_e32 v21, 0, v21
	v_max_f32_e32 v22, 0, v27
	s_mov_b64 s[18:19], 0x280000
	v_max_f32_e32 v24, 0, v24
	v_mul_f32_e32 v20, v20, v20
	v_mul_f32_e32 v21, v21, v21
	v_max_f32_e32 v23, 0, v23
	v_mul_f32_e32 v22, v22, v22
	v_lshl_add_u64 v[36:37], v[142:143], 0, s[18:19]
	v_mul_f32_e32 v24, v24, v24
	v_mul_f32_e32 v23, v23, v23
	v_cvt_pk_bf16_f32 v20, v24, v20
	v_cvt_pk_bf16_f32 v21, v21, v22
	v_cvt_pk_bf16_f32 v22, v28, v25
	v_max_f32_e32 v12, 0, v12
	v_cvt_pk_bf16_f32 v23, v26, v23
	global_store_dwordx4 v[36:37], v[20:23], off offset:256
	v_max_f32_e32 v13, 0, v13
	s_nop 0
	v_mul_f32_e32 v22, v12, v12
	v_max_f32_e32 v14, 0, v14
	v_max_f32_e32 v16, 0, v16
	v_max_f32_e32 v12, 0, v17
	v_mul_f32_e32 v17, v13, v13
	v_max_f32_e32 v13, v18, v18
	v_mul_f32_e32 v18, v14, v14
	v_mul_f32_e32 v16, v16, v16
	v_mul_f32_e32 v12, v12, v12
	v_max_f32_e32 v13, 0, v13
	v_max_f32_e32 v14, 0, v19
	s_mov_b32 s11, 0x2c0000
	v_mul_f32_e32 v13, v13, v13
	v_max_f32_e32 v15, 0, v15
	v_mul_f32_e32 v14, v14, v14
	v_cvt_pk_bf16_f32 v12, v16, v12
	v_add_co_u32_e32 v16, vcc, s11, v142
	v_mul_f32_e32 v15, v15, v15
	v_cvt_pk_bf16_f32 v13, v13, v14
	v_cvt_pk_bf16_f32 v14, v22, v17
	v_addc_co_u32_e32 v17, vcc, 0, v143, vcc
	v_max_f32_e32 v4, 0, v4
	v_max_f32_e32 v5, 0, v5
	v_max_f32_e32 v6, 0, v6
	v_cvt_pk_bf16_f32 v15, v18, v15
	global_store_dwordx4 v[16:17], v[12:15], off
	s_mov_b64 s[18:19], 0x2c0000
	s_nop 0
	v_mul_f32_e32 v12, v4, v4
	v_max_f32_e32 v4, v9, v9
	v_mul_f32_e32 v9, v5, v5
	v_max_f32_e32 v5, v10, v10
	v_mul_f32_e32 v10, v6, v6
	v_max_f32_e32 v4, 0, v4
	v_max_f32_e32 v5, 0, v5
	v_max_f32_e32 v6, 0, v11
	v_max_f32_e32 v7, 0, v7
	v_readlane_b32 s54, v250, 52
	v_lshl_add_u64 v[20:21], v[142:143], 0, s[18:19]
	v_max_f32_e32 v8, 0, v8
	v_mul_f32_e32 v4, v4, v4
	v_mul_f32_e32 v5, v5, v5
	v_mul_f32_e32 v6, v6, v6
	v_mul_f32_e32 v7, v7, v7
	s_andn2_b64 vcc, exec, s[40:41]
	s_mov_b64 s[18:19], -1
	s_mov_b64 s[56:57], 0x40000
	v_readlane_b32 s55, v250, 53
	v_mul_f32_e32 v8, v8, v8
	v_cvt_pk_bf16_f32 v4, v8, v4
	v_cvt_pk_bf16_f32 v5, v5, v6
	v_cvt_pk_bf16_f32 v6, v12, v9
	v_cvt_pk_bf16_f32 v7, v10, v7
	global_store_dwordx4 v[20:21], v[4:7], off offset:256

.Llast_ff1:
	v_max_f32_e32 v124, v124, v124
	v_lshl_add_u32 v148, s48, 8, v1
	v_max_f32_e32 v124, 0, v124
	v_max_f32_e32 v125, v125, v125
	v_max_f32_e32 v126, v126, v126
	v_lshl_or_b32 v142, s47, 8, v145
	v_ashrrev_i32_e32 v149, 31, v148
	v_readlane_b32 s2, v246, 29
	v_mul_f32_e32 v147, v124, v124
	v_max_f32_e32 v124, v129, v129
	v_max_f32_e32 v125, 0, v125
	v_max_f32_e32 v126, 0, v126
	v_ashrrev_i32_e32 v143, 31, v142
	v_lshlrev_b64 v[150:151], 14, v[148:149]
	v_readlane_b32 s3, v246, 30
	v_max_f32_e32 v124, 0, v124
	v_mul_f32_e32 v129, v125, v125
	v_max_f32_e32 v125, v130, v130
	v_mul_f32_e32 v130, v126, v126
	v_lshl_add_u64 v[150:151], s[2:3], 0, v[150:151]
	v_lshlrev_b64 v[152:153], 1, v[142:143]
	v_max_f32_e32 v128, 0, v128
	v_mul_f32_e32 v124, v124, v124
	v_max_f32_e32 v125, 0, v125
	v_max_f32_e32 v126, 0, v131
	v_max_f32_e32 v127, 0, v127
	v_lshl_add_u64 v[142:143], v[150:151], 0, v[152:153]
	v_mul_f32_e32 v128, v128, v128
	v_mul_f32_e32 v125, v125, v125
	v_mul_f32_e32 v126, v126, v126
	v_mul_f32_e32 v127, v127, v127
	v_cvt_pk_bf16_f32 v124, v128, v124
	v_max_f32_e32 v116, 0, v116
	v_cvt_pk_bf16_f32 v125, v125, v126
	v_cvt_pk_bf16_f32 v126, v147, v129
	v_cvt_pk_bf16_f32 v127, v130, v127
	global_store_dwordx4 v[142:143], v[124:127], off sc0 sc1
	v_max_f32_e32 v117, 0, v117
	v_max_f32_e32 v118, 0, v118
	v_mul_f32_e32 v124, v116, v116
	v_max_f32_e32 v116, 0, v121
	v_mul_f32_e32 v121, v117, v117
	v_max_f32_e32 v117, v122, v122
	v_mul_f32_e32 v122, v118, v118
	v_max_f32_e32 v120, 0, v120
	v_mul_f32_e32 v116, v116, v116
	v_max_f32_e32 v117, 0, v117
	v_max_f32_e32 v118, 0, v123
	v_max_f32_e32 v119, 0, v119
	v_mul_f32_e32 v120, v120, v120
	v_mul_f32_e32 v117, v117, v117
	v_mul_f32_e32 v118, v118, v118
	v_mul_f32_e32 v119, v119, v119
	v_cvt_pk_bf16_f32 v116, v120, v116
	v_cvt_pk_bf16_f32 v117, v117, v118
	v_cvt_pk_bf16_f32 v118, v124, v121
	v_cvt_pk_bf16_f32 v119, v122, v119
	global_store_dwordx4 v[142:143], v[116:119], off offset:256 sc0 sc1
	v_max_f32_e32 v108, 0, v108
	s_nop 0
	v_or_b32_e32 v116, 16, v148
	v_ashrrev_i32_e32 v117, 31, v116
	v_mul_f32_e32 v118, v108, v108
	v_max_f32_e32 v109, 0, v109
	v_max_f32_e32 v110, 0, v110
	v_lshlrev_b64 v[116:117], 14, v[116:117]
	v_max_f32_e32 v108, 0, v113
	v_mul_f32_e32 v113, v109, v109
	v_max_f32_e32 v109, v114, v114
	v_mul_f32_e32 v114, v110, v110
	v_lshl_add_u64 v[116:117], s[2:3], 0, v[116:117]
	v_max_f32_e32 v112, 0, v112
	v_mul_f32_e32 v108, v108, v108
	v_max_f32_e32 v109, 0, v109
	v_max_f32_e32 v110, 0, v115
	v_max_f32_e32 v111, 0, v111
	v_lshl_add_u64 v[116:117], v[116:117], 0, v[152:153]
	v_mul_f32_e32 v112, v112, v112
	v_mul_f32_e32 v109, v109, v109
	v_mul_f32_e32 v110, v110, v110
	v_mul_f32_e32 v111, v111, v111
	v_cvt_pk_bf16_f32 v108, v112, v108
	v_max_f32_e32 v100, 0, v100
	v_cvt_pk_bf16_f32 v109, v109, v110
	v_cvt_pk_bf16_f32 v110, v118, v113
	v_cvt_pk_bf16_f32 v111, v114, v111
	global_store_dwordx4 v[116:117], v[108:111], off sc0 sc1
	v_max_f32_e32 v101, 0, v101
	v_max_f32_e32 v102, 0, v102
	v_mul_f32_e32 v108, v100, v100
	v_max_f32_e32 v100, 0, v105
	v_mul_f32_e32 v105, v101, v101
	v_max_f32_e32 v101, v106, v106
	v_mul_f32_e32 v106, v102, v102
	v_max_f32_e32 v104, 0, v104
	v_mul_f32_e32 v100, v100, v100
	v_max_f32_e32 v101, 0, v101
	v_max_f32_e32 v102, 0, v107
	v_max_f32_e32 v103, 0, v103
	v_mul_f32_e32 v104, v104, v104
	v_mul_f32_e32 v101, v101, v101
	v_mul_f32_e32 v102, v102, v102
	v_mul_f32_e32 v103, v103, v103
	v_cvt_pk_bf16_f32 v100, v104, v100
	v_cvt_pk_bf16_f32 v101, v101, v102
	v_cvt_pk_bf16_f32 v102, v108, v105
	v_cvt_pk_bf16_f32 v103, v106, v103
	global_store_dwordx4 v[116:117], v[100:103], off offset:256 sc0 sc1
	v_max_f32_e32 v92, 0, v92
	s_nop 0
	v_or_b32_e32 v100, 32, v148
	v_ashrrev_i32_e32 v101, 31, v100
	v_mul_f32_e32 v102, v92, v92
	v_max_f32_e32 v93, 0, v93
	v_max_f32_e32 v94, 0, v94
	v_lshlrev_b64 v[100:101], 14, v[100:101]
	v_max_f32_e32 v92, 0, v97
	v_mul_f32_e32 v97, v93, v93
	v_max_f32_e32 v93, v98, v98
	v_mul_f32_e32 v98, v94, v94
	v_lshl_add_u64 v[100:101], s[2:3], 0, v[100:101]
	v_max_f32_e32 v96, 0, v96
	v_mul_f32_e32 v92, v92, v92
	v_max_f32_e32 v93, 0, v93
	v_max_f32_e32 v94, 0, v99
	v_max_f32_e32 v95, 0, v95
	v_lshl_add_u64 v[100:101], v[100:101], 0, v[152:153]
	v_mul_f32_e32 v96, v96, v96
	v_mul_f32_e32 v93, v93, v93
	v_mul_f32_e32 v94, v94, v94
	v_mul_f32_e32 v95, v95, v95
	v_cvt_pk_bf16_f32 v92, v96, v92
	v_max_f32_e32 v84, 0, v84
	v_cvt_pk_bf16_f32 v93, v93, v94
	v_cvt_pk_bf16_f32 v94, v102, v97
	v_cvt_pk_bf16_f32 v95, v98, v95
	global_store_dwordx4 v[100:101], v[92:95], off sc0 sc1
	v_max_f32_e32 v85, 0, v85
	v_max_f32_e32 v86, 0, v86
	v_mul_f32_e32 v92, v84, v84
	v_max_f32_e32 v84, 0, v89
	v_mul_f32_e32 v89, v85, v85
	v_max_f32_e32 v85, v90, v90
	v_mul_f32_e32 v90, v86, v86
	v_max_f32_e32 v88, 0, v88
	v_mul_f32_e32 v84, v84, v84
	v_max_f32_e32 v85, 0, v85
	v_max_f32_e32 v86, 0, v91
	v_max_f32_e32 v87, 0, v87
	v_mul_f32_e32 v88, v88, v88
	v_mul_f32_e32 v85, v85, v85
	v_mul_f32_e32 v86, v86, v86
	v_mul_f32_e32 v87, v87, v87
	v_cvt_pk_bf16_f32 v84, v88, v84
	v_cvt_pk_bf16_f32 v85, v85, v86
	v_cvt_pk_bf16_f32 v86, v92, v89
	v_cvt_pk_bf16_f32 v87, v90, v87
	global_store_dwordx4 v[100:101], v[84:87], off offset:256 sc0 sc1
	v_max_f32_e32 v76, 0, v76
	s_nop 0
	v_or_b32_e32 v84, 48, v148
	v_ashrrev_i32_e32 v85, 31, v84
	v_mul_f32_e32 v86, v76, v76
	v_max_f32_e32 v77, 0, v77
	v_max_f32_e32 v78, 0, v78
	v_lshlrev_b64 v[84:85], 14, v[84:85]
	v_max_f32_e32 v76, 0, v81
	v_mul_f32_e32 v81, v77, v77
	v_max_f32_e32 v77, v82, v82
	v_mul_f32_e32 v82, v78, v78
	v_lshl_add_u64 v[84:85], s[2:3], 0, v[84:85]
	v_max_f32_e32 v80, 0, v80
	v_mul_f32_e32 v76, v76, v76
	v_max_f32_e32 v77, 0, v77
	v_max_f32_e32 v78, 0, v83
	v_max_f32_e32 v79, 0, v79
	v_lshl_add_u64 v[84:85], v[84:85], 0, v[152:153]
	v_mul_f32_e32 v80, v80, v80
	v_mul_f32_e32 v77, v77, v77
	v_mul_f32_e32 v78, v78, v78
	v_mul_f32_e32 v79, v79, v79
	v_cvt_pk_bf16_f32 v76, v80, v76
	v_max_f32_e32 v68, 0, v68
	v_max_f32_e32 v69, 0, v69
	v_max_f32_e32 v70, 0, v70
	v_cvt_pk_bf16_f32 v77, v77, v78
	v_cvt_pk_bf16_f32 v78, v86, v81
	v_cvt_pk_bf16_f32 v79, v82, v79
	global_store_dwordx4 v[84:85], v[76:79], off sc0 sc1
	s_nop 1
	v_mul_f32_e32 v76, v68, v68
	v_max_f32_e32 v68, v73, v73
	v_mul_f32_e32 v73, v69, v69
	v_max_f32_e32 v69, v74, v74
	v_mul_f32_e32 v74, v70, v70
	v_max_f32_e32 v68, 0, v68
	v_max_f32_e32 v69, 0, v69
	v_max_f32_e32 v70, 0, v75
	v_max_f32_e32 v72, 0, v72
	v_mul_f32_e32 v68, v68, v68
	v_mul_f32_e32 v69, v69, v69
	v_max_f32_e32 v71, 0, v71
	v_mul_f32_e32 v70, v70, v70
	v_mul_f32_e32 v72, v72, v72
	v_mul_f32_e32 v71, v71, v71
	v_cvt_pk_bf16_f32 v68, v72, v68
	v_cvt_pk_bf16_f32 v69, v69, v70
	v_cvt_pk_bf16_f32 v70, v76, v73
	v_max_f32_e32 v60, 0, v60
	v_cvt_pk_bf16_f32 v71, v74, v71
	global_store_dwordx4 v[84:85], v[68:71], off offset:256 sc0 sc1
	v_max_f32_e32 v61, 0, v61
	s_nop 0
	v_mul_f32_e32 v70, v60, v60
	v_max_f32_e32 v62, 0, v62
	v_max_f32_e32 v64, 0, v64
	v_max_f32_e32 v60, 0, v65
	v_mul_f32_e32 v65, v61, v61
	v_max_f32_e32 v61, v66, v66
	v_mul_f32_e32 v66, v62, v62
	v_mul_f32_e32 v64, v64, v64
	v_mul_f32_e32 v60, v60, v60
	v_max_f32_e32 v61, 0, v61
	v_max_f32_e32 v62, 0, v67
	s_mov_b32 s11, 0x200000
	v_mul_f32_e32 v61, v61, v61
	v_max_f32_e32 v63, 0, v63
	v_mul_f32_e32 v62, v62, v62
	v_cvt_pk_bf16_f32 v60, v64, v60
	v_add_co_u32_e32 v64, vcc, s11, v142
	v_mul_f32_e32 v63, v63, v63
	v_cvt_pk_bf16_f32 v61, v61, v62
	v_cvt_pk_bf16_f32 v62, v70, v65
	v_addc_co_u32_e32 v65, vcc, 0, v143, vcc
	v_max_f32_e32 v52, 0, v52
	v_max_f32_e32 v53, 0, v53
	v_max_f32_e32 v54, 0, v54
	v_cvt_pk_bf16_f32 v63, v66, v63
	global_store_dwordx4 v[64:65], v[60:63], off sc0 sc1
	s_nop 1
	v_mul_f32_e32 v60, v52, v52
	v_max_f32_e32 v52, v57, v57
	v_mul_f32_e32 v57, v53, v53
	v_max_f32_e32 v53, v58, v58
	v_mul_f32_e32 v58, v54, v54
	v_max_f32_e32 v52, 0, v52
	v_max_f32_e32 v53, 0, v53
	v_max_f32_e32 v54, 0, v59
	s_mov_b64 s[18:19], 0x200000
	v_max_f32_e32 v56, 0, v56
	v_mul_f32_e32 v52, v52, v52
	v_mul_f32_e32 v53, v53, v53
	v_max_f32_e32 v55, 0, v55
	v_mul_f32_e32 v54, v54, v54
	v_lshl_add_u64 v[68:69], v[142:143], 0, s[18:19]
	v_mul_f32_e32 v56, v56, v56
	v_mul_f32_e32 v55, v55, v55
	v_cvt_pk_bf16_f32 v52, v56, v52
	v_cvt_pk_bf16_f32 v53, v53, v54
	v_cvt_pk_bf16_f32 v54, v60, v57
	v_max_f32_e32 v44, 0, v44
	v_cvt_pk_bf16_f32 v55, v58, v55
	global_store_dwordx4 v[68:69], v[52:55], off offset:256 sc0 sc1
	v_max_f32_e32 v45, 0, v45
	s_nop 0
	v_mul_f32_e32 v54, v44, v44
	v_max_f32_e32 v46, 0, v46
	v_max_f32_e32 v48, 0, v48
	v_max_f32_e32 v44, 0, v49
	v_mul_f32_e32 v49, v45, v45
	v_max_f32_e32 v45, v50, v50
	v_mul_f32_e32 v50, v46, v46
	v_mul_f32_e32 v48, v48, v48
	v_mul_f32_e32 v44, v44, v44
	v_max_f32_e32 v45, 0, v45
	v_max_f32_e32 v46, 0, v51
	s_mov_b32 s11, 0x240000
	v_mul_f32_e32 v45, v45, v45
	v_max_f32_e32 v47, 0, v47
	v_mul_f32_e32 v46, v46, v46
	v_cvt_pk_bf16_f32 v44, v48, v44
	v_add_co_u32_e32 v48, vcc, s11, v142
	v_mul_f32_e32 v47, v47, v47
	v_cvt_pk_bf16_f32 v45, v45, v46
	v_cvt_pk_bf16_f32 v46, v54, v49
	v_addc_co_u32_e32 v49, vcc, 0, v143, vcc
	v_max_f32_e32 v36, 0, v36
	v_max_f32_e32 v37, 0, v37
	v_max_f32_e32 v38, 0, v38
	v_cvt_pk_bf16_f32 v47, v50, v47
	global_store_dwordx4 v[48:49], v[44:47], off sc0 sc1
	s_nop 1
	v_mul_f32_e32 v44, v36, v36
	v_max_f32_e32 v36, v41, v41
	v_mul_f32_e32 v41, v37, v37
	v_max_f32_e32 v37, v42, v42
	v_mul_f32_e32 v42, v38, v38
	v_max_f32_e32 v36, 0, v36
	v_max_f32_e32 v37, 0, v37
	v_max_f32_e32 v38, 0, v43
	s_mov_b64 s[18:19], 0x240000
	v_max_f32_e32 v40, 0, v40
	v_mul_f32_e32 v36, v36, v36
	v_mul_f32_e32 v37, v37, v37
	v_max_f32_e32 v39, 0, v39
	v_mul_f32_e32 v38, v38, v38
	v_lshl_add_u64 v[52:53], v[142:143], 0, s[18:19]
	v_mul_f32_e32 v40, v40, v40
	v_mul_f32_e32 v39, v39, v39
	v_cvt_pk_bf16_f32 v36, v40, v36
	v_cvt_pk_bf16_f32 v37, v37, v38
	v_cvt_pk_bf16_f32 v38, v44, v41
	v_max_f32_e32 v28, 0, v28
	v_cvt_pk_bf16_f32 v39, v42, v39
	global_store_dwordx4 v[52:53], v[36:39], off offset:256 sc0 sc1
	v_max_f32_e32 v29, 0, v29
	s_nop 0
	v_mul_f32_e32 v38, v28, v28
	v_max_f32_e32 v30, 0, v30
	v_max_f32_e32 v32, 0, v32
	v_max_f32_e32 v28, 0, v33
	v_mul_f32_e32 v33, v29, v29
	v_max_f32_e32 v29, v34, v34
	v_mul_f32_e32 v34, v30, v30
	v_mul_f32_e32 v32, v32, v32
	v_mul_f32_e32 v28, v28, v28
	v_max_f32_e32 v29, 0, v29
	v_max_f32_e32 v30, 0, v35
	s_mov_b32 s11, 0x280000
	v_mul_f32_e32 v29, v29, v29
	v_max_f32_e32 v31, 0, v31
	v_mul_f32_e32 v30, v30, v30
	v_cvt_pk_bf16_f32 v28, v32, v28
	v_add_co_u32_e32 v32, vcc, s11, v142
	v_mul_f32_e32 v31, v31, v31
	v_cvt_pk_bf16_f32 v29, v29, v30
	v_cvt_pk_bf16_f32 v30, v38, v33
	v_addc_co_u32_e32 v33, vcc, 0, v143, vcc
	v_max_f32_e32 v20, 0, v20
	v_max_f32_e32 v21, 0, v21
	v_max_f32_e32 v22, 0, v22
	v_cvt_pk_bf16_f32 v31, v34, v31
	global_store_dwordx4 v[32:33], v[28:31], off sc0 sc1
	s_nop 1
	v_mul_f32_e32 v28, v20, v20
	v_max_f32_e32 v20, v25, v25
	v_mul_f32_e32 v25, v21, v21
	v_max_f32_e32 v21, v26, v26
	v_mul_f32_e32 v26, v22, v22
	v_max_f32_e32 v20, 0, v20
	v_max_f32_e32 v21, 0, v21
	v_max_f32_e32 v22, 0, v27
	s_mov_b64 s[18:19], 0x280000
	v_max_f32_e32 v24, 0, v24
	v_mul_f32_e32 v20, v20, v20
	v_mul_f32_e32 v21, v21, v21
	v_max_f32_e32 v23, 0, v23
	v_mul_f32_e32 v22, v22, v22
	v_lshl_add_u64 v[36:37], v[142:143], 0, s[18:19]
	v_mul_f32_e32 v24, v24, v24
	v_mul_f32_e32 v23, v23, v23
	v_cvt_pk_bf16_f32 v20, v24, v20
	v_cvt_pk_bf16_f32 v21, v21, v22
	v_cvt_pk_bf16_f32 v22, v28, v25
	v_max_f32_e32 v12, 0, v12
	v_cvt_pk_bf16_f32 v23, v26, v23
	global_store_dwordx4 v[36:37], v[20:23], off offset:256 sc0 sc1
	v_max_f32_e32 v13, 0, v13
	s_nop 0
	v_mul_f32_e32 v22, v12, v12
	v_max_f32_e32 v14, 0, v14
	v_max_f32_e32 v16, 0, v16
	v_max_f32_e32 v12, 0, v17
	v_mul_f32_e32 v17, v13, v13
	v_max_f32_e32 v13, v18, v18
	v_mul_f32_e32 v18, v14, v14
	v_mul_f32_e32 v16, v16, v16
	v_mul_f32_e32 v12, v12, v12
	v_max_f32_e32 v13, 0, v13
	v_max_f32_e32 v14, 0, v19
	s_mov_b32 s11, 0x2c0000
	v_mul_f32_e32 v13, v13, v13
	v_max_f32_e32 v15, 0, v15
	v_mul_f32_e32 v14, v14, v14
	v_cvt_pk_bf16_f32 v12, v16, v12
	v_add_co_u32_e32 v16, vcc, s11, v142
	v_mul_f32_e32 v15, v15, v15
	v_cvt_pk_bf16_f32 v13, v13, v14
	v_cvt_pk_bf16_f32 v14, v22, v17
	v_addc_co_u32_e32 v17, vcc, 0, v143, vcc
	v_max_f32_e32 v4, 0, v4
	v_max_f32_e32 v5, 0, v5
	v_max_f32_e32 v6, 0, v6
	v_cvt_pk_bf16_f32 v15, v18, v15
	global_store_dwordx4 v[16:17], v[12:15], off sc0 sc1
	s_mov_b64 s[18:19], 0x2c0000
	s_nop 0
	v_mul_f32_e32 v12, v4, v4
	v_max_f32_e32 v4, v9, v9
	v_mul_f32_e32 v9, v5, v5
	v_max_f32_e32 v5, v10, v10
	v_mul_f32_e32 v10, v6, v6
	v_max_f32_e32 v4, 0, v4
	v_max_f32_e32 v5, 0, v5
	v_max_f32_e32 v6, 0, v11
	v_max_f32_e32 v7, 0, v7
	v_readlane_b32 s54, v250, 52
	v_lshl_add_u64 v[20:21], v[142:143], 0, s[18:19]
	v_max_f32_e32 v8, 0, v8
	v_mul_f32_e32 v4, v4, v4
	v_mul_f32_e32 v5, v5, v5
	v_mul_f32_e32 v6, v6, v6
	v_mul_f32_e32 v7, v7, v7
	s_andn2_b64 vcc, exec, s[40:41]
	s_mov_b64 s[18:19], -1
	s_mov_b64 s[56:57], 0x40000
	v_readlane_b32 s55, v250, 53
	v_mul_f32_e32 v8, v8, v8
	v_cvt_pk_bf16_f32 v4, v8, v4
	v_cvt_pk_bf16_f32 v5, v5, v6
	v_cvt_pk_bf16_f32 v6, v12, v9
	v_cvt_pk_bf16_f32 v7, v10, v7
	global_store_dwordx4 v[20:21], v[4:7], off offset:256 sc0 sc1
	s_branch .Ljoin_ff1
